# P10 W_in GEMM epilogue: 8 row-bias loads batched up front, no per-row vmcnt(0)
# baseline (speedup 1.0000x reference)
; __device__ __forceinline__ unsigned pk2(float lo, float hi) { f32x2 v = {lo, hi}; bf16x2_t b = __builtin_convertvector(v, bf16x2_t); return __builtin_bit_cast(unsigned, b); }
;     __device__ __forceinline__ void operator()(const f32x4 (&acc)[2][2][4][2], const Unit& u, int wr, int wc, int fr, int fq) const {
;         const int row0 = u.pm * BM + wr * 64 + fr; const int col0 = u.pn * BM + wc * 32 + 8 * fq;
; #pragma unroll
;         for (int ai = 0; ai < 2; ++ai)
; #pragma unroll
;             for (int m = 0; m < 4; ++m) { const int row = row0 + ai * HALF + m * 16; const float rb = rowbias ? rowbias[row] : 0.f; bf16_t* rowp = O + (size_t)row * ldc + col0;
; #pragma unroll
;                 for (int bj = 0; bj < 2; ++bj) { const f32x4 v0 = acc[ai][bj][m][0] + rb, v1 = acc[ai][bj][m][1] + rb;
;                     u32x4 w; w.x = pk2(v0[0], v0[1]); w.y = pk2(v0[2], v0[3]); w.z = pk2(v1[0], v1[1]); w.w = pk2(v1[2], v1[3]);
;                     *(u32x4*)(rowp + bj * HALF) = w; } }
.LBB0_918:
	v_lshl_add_u32 v148, s4, 8, v155
	v_readlane_b32 s80, v255, 4
	v_ashrrev_i32_e32 v149, 31, v148
	v_cndmask_b32_e64 v144, 0, 1, s[12:13]
	v_readlane_b32 s92, v255, 16
	v_readlane_b32 s93, v255, 17
	v_mov_b32_e32 v154, 0
	v_cmp_ne_u32_e64 s[4:5], 1, v144
	s_andn2_b64 vcc, exec, s[12:13]
	v_lshl_add_u64 v[146:147], v[148:149], 2, s[92:93]
	v_mov_b32_e32 v156, 0
	v_readlane_b32 s81, v255, 5
	v_readlane_b32 s82, v255, 6
	v_readlane_b32 s83, v255, 7
	v_readlane_b32 s84, v255, 8
	v_readlane_b32 s85, v255, 9
	v_readlane_b32 s86, v255, 10
	v_readlane_b32 s87, v255, 11
	v_readlane_b32 s88, v255, 12
	v_readlane_b32 s89, v255, 13
	v_readlane_b32 s90, v255, 14
	v_readlane_b32 s91, v255, 15
	v_readlane_b32 s94, v255, 18
	v_readlane_b32 s95, v255, 19
	v_mov_b32_e32 v177, 0
	v_mov_b32_e32 v178, 0
	v_mov_b32_e32 v179, 0
	v_mov_b32_e32 v180, 0
	v_mov_b32_e32 v181, 0
	v_mov_b32_e32 v182, 0
	v_mov_b32_e32 v183, 0
	s_cbranch_vccnz .LBB0_920
	global_load_dword v156, v[146:147], off
	global_load_dword v177, v[146:147], off offset:64
	global_load_dword v178, v[146:147], off offset:128
	global_load_dword v179, v[146:147], off offset:192
	global_load_dword v180, v[146:147], off offset:512
	global_load_dword v181, v[146:147], off offset:576
	global_load_dword v182, v[146:147], off offset:640
	global_load_dword v183, v[146:147], off offset:704
.LBB0_920:
	v_lshl_or_b32 v150, s52, 8, v158
	v_lshlrev_b64 v[144:145], 17, v[148:149]
	v_ashrrev_i32_e32 v151, 31, v150
	v_lshl_add_u64 v[144:145], s[10:11], 0, v[144:145]
	s_waitcnt vmcnt(0)
	v_pk_add_f32 v[126:127], v[126:127], v[156:157] op_sel_hi:[1,0]
	v_pk_add_f32 v[124:125], v[124:125], v[156:157] op_sel_hi:[1,0]
	v_pk_add_f32 v[162:163], v[122:123], v[156:157] op_sel_hi:[1,0]
	v_pk_add_f32 v[122:123], v[120:121], v[156:157] op_sel_hi:[1,0]
	v_lshl_add_u64 v[144:145], v[150:151], 1, v[144:145]
	v_cvt_pk_bf16_f32 v120, v124, v125
	v_cvt_pk_bf16_f32 v121, v126, v127
	v_cvt_pk_bf16_f32 v122, v122, v123
	v_cvt_pk_bf16_f32 v123, v162, v163
	global_store_dwordx4 v[144:145], v[120:123], off
	v_pk_add_f32 v[118:119], v[118:119], v[156:157] op_sel_hi:[1,0]
	v_pk_add_f32 v[116:117], v[116:117], v[156:157] op_sel_hi:[1,0]
	v_pk_add_f32 v[120:121], v[114:115], v[156:157] op_sel_hi:[1,0]
	v_pk_add_f32 v[114:115], v[112:113], v[156:157] op_sel_hi:[1,0]
	v_cvt_pk_bf16_f32 v112, v116, v117
	v_cvt_pk_bf16_f32 v113, v118, v119
	v_cvt_pk_bf16_f32 v114, v114, v115
	v_cvt_pk_bf16_f32 v115, v120, v121
	s_and_b64 vcc, exec, s[4:5]
	global_store_dwordx4 v[144:145], v[112:115], off offset:256
	v_mov_b32_e32 v154, v177
.LBB0_922:
	s_nop 0
	v_or_b32_e32 v112, 16, v148
	v_ashrrev_i32_e32 v113, 31, v112
	v_lshlrev_b64 v[112:113], 17, v[112:113]
	v_lshl_add_u64 v[112:113], s[10:11], 0, v[112:113]
	s_nop 0
	v_pk_add_f32 v[110:111], v[110:111], v[154:155] op_sel_hi:[1,0]
	v_pk_add_f32 v[108:109], v[108:109], v[154:155] op_sel_hi:[1,0]
	v_pk_add_f32 v[114:115], v[106:107], v[154:155] op_sel_hi:[1,0]
	v_pk_add_f32 v[106:107], v[104:105], v[154:155] op_sel_hi:[1,0]
	v_lshl_add_u64 v[112:113], v[150:151], 1, v[112:113]
	v_cvt_pk_bf16_f32 v104, v108, v109
	v_cvt_pk_bf16_f32 v105, v110, v111
	v_cvt_pk_bf16_f32 v106, v106, v107
	v_cvt_pk_bf16_f32 v107, v114, v115
	global_store_dwordx4 v[112:113], v[104:107], off
	v_pk_add_f32 v[102:103], v[102:103], v[154:155] op_sel_hi:[1,0]
	v_pk_add_f32 v[100:101], v[100:101], v[154:155] op_sel_hi:[1,0]
	v_pk_add_f32 v[104:105], v[98:99], v[154:155] op_sel_hi:[1,0]
	v_pk_add_f32 v[98:99], v[96:97], v[154:155] op_sel_hi:[1,0]
	v_cvt_pk_bf16_f32 v96, v100, v101
	v_cvt_pk_bf16_f32 v97, v102, v103
	v_cvt_pk_bf16_f32 v98, v98, v99
	v_cvt_pk_bf16_f32 v99, v104, v105
	global_store_dwordx4 v[112:113], v[96:99], off offset:256
	s_and_b64 vcc, exec, s[4:5]
	s_nop 0
	v_mov_b32_e32 v96, 0
	v_mov_b32_e32 v98, 0
	v_mov_b32_e32 v98, v178
.LBB0_924:
	v_or_b32_e32 v100, 32, v148
	v_ashrrev_i32_e32 v101, 31, v100
	v_lshlrev_b64 v[100:101], 17, v[100:101]
	v_lshl_add_u64 v[100:101], s[10:11], 0, v[100:101]
	s_nop 0
	v_pk_add_f32 v[94:95], v[94:95], v[98:99] op_sel_hi:[1,0]
	v_pk_add_f32 v[92:93], v[92:93], v[98:99] op_sel_hi:[1,0]
	v_pk_add_f32 v[102:103], v[90:91], v[98:99] op_sel_hi:[1,0]
	v_pk_add_f32 v[90:91], v[88:89], v[98:99] op_sel_hi:[1,0]
	v_lshl_add_u64 v[100:101], v[150:151], 1, v[100:101]
	v_cvt_pk_bf16_f32 v88, v92, v93
	v_cvt_pk_bf16_f32 v89, v94, v95
	v_cvt_pk_bf16_f32 v90, v90, v91
	v_cvt_pk_bf16_f32 v91, v102, v103
	global_store_dwordx4 v[100:101], v[88:91], off
	v_pk_add_f32 v[86:87], v[86:87], v[98:99] op_sel_hi:[1,0]
	v_pk_add_f32 v[84:85], v[84:85], v[98:99] op_sel_hi:[1,0]
	v_pk_add_f32 v[88:89], v[82:83], v[98:99] op_sel_hi:[1,0]
	v_pk_add_f32 v[82:83], v[80:81], v[98:99] op_sel_hi:[1,0]
	v_cvt_pk_bf16_f32 v80, v84, v85
	v_cvt_pk_bf16_f32 v81, v86, v87
	v_cvt_pk_bf16_f32 v82, v82, v83
	v_cvt_pk_bf16_f32 v83, v88, v89
	s_and_b64 vcc, exec, s[4:5]
	global_store_dwordx4 v[100:101], v[80:83], off offset:256
	v_mov_b32_e32 v96, v179
; __device__ __forceinline__ unsigned pk2(float lo, float hi) { f32x2 v = {lo, hi}; bf16x2_t b = __builtin_convertvector(v, bf16x2_t); return __builtin_bit_cast(unsigned, b); }
;     __device__ __forceinline__ void operator()(const f32x4 (&acc)[2][2][4][2], const Unit& u, int wr, int wc, int fr, int fq) const {
;         const int row0 = u.pm * BM + wr * 64 + fr; const int col0 = u.pn * BM + wc * 32 + 8 * fq;
; #pragma unroll
;         for (int ai = 0; ai < 2; ++ai)
; #pragma unroll
;             for (int m = 0; m < 4; ++m) { const int row = row0 + ai * HALF + m * 16; const float rb = rowbias ? rowbias[row] : 0.f; bf16_t* rowp = O + (size_t)row * ldc + col0;
; #pragma unroll
;                 for (int bj = 0; bj < 2; ++bj) { const f32x4 v0 = acc[ai][bj][m][0] + rb, v1 = acc[ai][bj][m][1] + rb;
;                     u32x4 w; w.x = pk2(v0[0], v0[1]); w.y = pk2(v0[2], v0[3]); w.z = pk2(v1[0], v1[1]); w.w = pk2(v1[2], v1[3]);
;                     *(u32x4*)(rowp + bj * HALF) = w; } }
.LBB0_926:
	s_nop 0
	v_or_b32_e32 v80, 48, v148
	v_ashrrev_i32_e32 v81, 31, v80
	v_lshlrev_b64 v[80:81], 17, v[80:81]
	v_lshl_add_u64 v[80:81], s[10:11], 0, v[80:81]
	s_nop 0
	v_pk_add_f32 v[78:79], v[78:79], v[96:97] op_sel_hi:[1,0]
	v_pk_add_f32 v[76:77], v[76:77], v[96:97] op_sel_hi:[1,0]
	v_pk_add_f32 v[82:83], v[74:75], v[96:97] op_sel_hi:[1,0]
	v_pk_add_f32 v[74:75], v[72:73], v[96:97] op_sel_hi:[1,0]
	v_lshl_add_u64 v[80:81], v[150:151], 1, v[80:81]
	v_cvt_pk_bf16_f32 v72, v76, v77
	v_cvt_pk_bf16_f32 v73, v78, v79
	v_cvt_pk_bf16_f32 v74, v74, v75
	v_cvt_pk_bf16_f32 v75, v82, v83
	global_store_dwordx4 v[80:81], v[72:75], off
	v_pk_add_f32 v[70:71], v[70:71], v[96:97] op_sel_hi:[1,0]
	v_pk_add_f32 v[68:69], v[68:69], v[96:97] op_sel_hi:[1,0]
	v_pk_add_f32 v[72:73], v[66:67], v[96:97] op_sel_hi:[1,0]
	v_pk_add_f32 v[66:67], v[64:65], v[96:97] op_sel_hi:[1,0]
	v_cvt_pk_bf16_f32 v64, v68, v69
	v_cvt_pk_bf16_f32 v65, v70, v71
	v_cvt_pk_bf16_f32 v66, v66, v67
	v_cvt_pk_bf16_f32 v67, v72, v73
	global_store_dwordx4 v[80:81], v[64:67], off offset:256
	s_and_b64 vcc, exec, s[4:5]
	s_nop 0
	v_mov_b32_e32 v64, 0
	v_mov_b32_e32 v66, 0
	v_mov_b32_e32 v66, v180
.LBB0_928:
	s_nop 0
	v_pk_add_f32 v[60:61], v[60:61], v[66:67] op_sel_hi:[1,0]
	v_pk_add_f32 v[62:63], v[62:63], v[66:67] op_sel_hi:[1,0]
	v_pk_add_f32 v[70:71], v[58:59], v[66:67] op_sel_hi:[1,0]
	v_pk_add_f32 v[58:59], v[56:57], v[66:67] op_sel_hi:[1,0]
	v_cvt_pk_bf16_f32 v56, v60, v61
	v_add_co_u32_e32 v60, vcc, s64, v144
	v_cvt_pk_bf16_f32 v57, v62, v63
	v_cvt_pk_bf16_f32 v58, v58, v59
	v_cvt_pk_bf16_f32 v59, v70, v71
	v_addc_co_u32_e32 v61, vcc, 0, v145, vcc
	global_store_dwordx4 v[60:61], v[56:59], off
	v_pk_add_f32 v[54:55], v[54:55], v[66:67] op_sel_hi:[1,0]
	v_pk_add_f32 v[52:53], v[52:53], v[66:67] op_sel_hi:[1,0]
	v_pk_add_f32 v[56:57], v[46:47], v[66:67] op_sel_hi:[1,0]
	v_pk_add_f32 v[46:47], v[44:45], v[66:67] op_sel_hi:[1,0]
	v_lshl_add_u64 v[68:69], v[144:145], 0, s[24:25]
	v_cvt_pk_bf16_f32 v44, v52, v53
	v_cvt_pk_bf16_f32 v45, v54, v55
	v_cvt_pk_bf16_f32 v46, v46, v47
	v_cvt_pk_bf16_f32 v47, v56, v57
	s_and_b64 vcc, exec, s[4:5]
	global_store_dwordx4 v[68:69], v[44:47], off offset:256
	v_mov_b32_e32 v64, v181
.LBB0_930:
	s_nop 0
	v_pk_add_f32 v[46:47], v[50:51], v[64:65] op_sel_hi:[1,0]
	v_pk_add_f32 v[48:49], v[48:49], v[64:65] op_sel_hi:[1,0]
	v_pk_add_f32 v[50:51], v[42:43], v[64:65] op_sel_hi:[1,0]
	v_pk_add_f32 v[42:43], v[40:41], v[64:65] op_sel_hi:[1,0]
	v_cvt_pk_bf16_f32 v41, v46, v47
	v_add_co_u32_e32 v46, vcc, s65, v144
	v_cvt_pk_bf16_f32 v40, v48, v49
	v_cvt_pk_bf16_f32 v42, v42, v43
	v_cvt_pk_bf16_f32 v43, v50, v51
	v_addc_co_u32_e32 v47, vcc, 0, v145, vcc
	global_store_dwordx4 v[46:47], v[40:43], off
	v_pk_add_f32 v[38:39], v[38:39], v[64:65] op_sel_hi:[1,0]
	v_pk_add_f32 v[36:37], v[36:37], v[64:65] op_sel_hi:[1,0]
	v_pk_add_f32 v[40:41], v[30:31], v[64:65] op_sel_hi:[1,0]
	v_pk_add_f32 v[30:31], v[28:29], v[64:65] op_sel_hi:[1,0]
	v_lshl_add_u64 v[44:45], v[144:145], 0, s[36:37]
	v_cvt_pk_bf16_f32 v28, v36, v37
	v_cvt_pk_bf16_f32 v29, v38, v39
	v_cvt_pk_bf16_f32 v30, v30, v31
	v_cvt_pk_bf16_f32 v31, v40, v41
	global_store_dwordx4 v[44:45], v[28:31], off offset:256
	s_and_b64 vcc, exec, s[4:5]
	s_nop 0
	v_mov_b32_e32 v28, 0
	v_mov_b32_e32 v30, 0
	v_mov_b32_e32 v30, v182
.LBB0_932:
	s_nop 0
	v_pk_add_f32 v[32:33], v[32:33], v[30:31] op_sel_hi:[1,0]
	v_pk_add_f32 v[34:35], v[34:35], v[30:31] op_sel_hi:[1,0]
	v_pk_add_f32 v[38:39], v[26:27], v[30:31] op_sel_hi:[1,0]
	v_pk_add_f32 v[26:27], v[24:25], v[30:31] op_sel_hi:[1,0]
	v_cvt_pk_bf16_f32 v24, v32, v33
	v_add_co_u32_e32 v32, vcc, s66, v144
	v_cvt_pk_bf16_f32 v25, v34, v35
	v_cvt_pk_bf16_f32 v26, v26, v27
	v_cvt_pk_bf16_f32 v27, v38, v39
	v_addc_co_u32_e32 v33, vcc, 0, v145, vcc
	global_store_dwordx4 v[32:33], v[24:27], off
	v_pk_add_f32 v[22:23], v[22:23], v[30:31] op_sel_hi:[1,0]
	v_pk_add_f32 v[20:21], v[20:21], v[30:31] op_sel_hi:[1,0]
	v_pk_add_f32 v[24:25], v[14:15], v[30:31] op_sel_hi:[1,0]
	v_pk_add_f32 v[14:15], v[12:13], v[30:31] op_sel_hi:[1,0]
	v_lshl_add_u64 v[36:37], v[144:145], 0, s[38:39]
	v_cvt_pk_bf16_f32 v12, v20, v21
	v_cvt_pk_bf16_f32 v13, v22, v23
	v_cvt_pk_bf16_f32 v14, v14, v15
	v_cvt_pk_bf16_f32 v15, v24, v25
	s_and_b64 vcc, exec, s[4:5]
	global_store_dwordx4 v[36:37], v[12:15], off offset:256
	v_mov_b32_e32 v28, v183
.LBB0_934:
	s_nop 0
	v_pk_add_f32 v[14:15], v[18:19], v[28:29] op_sel_hi:[1,0]
	v_pk_add_f32 v[16:17], v[16:17], v[28:29] op_sel_hi:[1,0]
	v_pk_add_f32 v[18:19], v[10:11], v[28:29] op_sel_hi:[1,0]
	v_pk_add_f32 v[10:11], v[8:9], v[28:29] op_sel_hi:[1,0]
	v_cvt_pk_bf16_f32 v9, v14, v15
	v_add_co_u32_e32 v14, vcc, s67, v144
	v_cvt_pk_bf16_f32 v8, v16, v17
	v_cvt_pk_bf16_f32 v10, v10, v11
	v_cvt_pk_bf16_f32 v11, v18, v19
	v_addc_co_u32_e32 v15, vcc, 0, v145, vcc
	global_store_dwordx4 v[14:15], v[8:11], off
	v_pk_add_f32 v[6:7], v[6:7], v[28:29] op_sel_hi:[1,0]
	v_pk_add_f32 v[4:5], v[4:5], v[28:29] op_sel_hi:[1,0]
	v_pk_add_f32 v[8:9], v[2:3], v[28:29] op_sel_hi:[1,0]
	v_pk_add_f32 v[2:3], v[0:1], v[28:29] op_sel_hi:[1,0]
	v_lshl_add_u64 v[12:13], v[144:145], 0, s[40:41]
	v_cvt_pk_bf16_f32 v0, v4, v5
	v_cvt_pk_bf16_f32 v1, v6, v7
	v_cvt_pk_bf16_f32 v2, v2, v3
	v_cvt_pk_bf16_f32 v3, v8, v9
	s_andn2_b64 vcc, exec, s[0:1]
	s_mov_b64 s[0:1], -1
	global_store_dwordx4 v[12:13], v[0:3], off offset:256
	s_cbranch_vccnz .LBB0_911
	s_andn2_b64 vcc, exec, s[8:9]
	s_cbranch_vccnz .LBB0_910
	s_barrier
	s_branch .LBB0_910
